# s5c: LDS operand reads pipelined 3-deep through a 4-buffer ring in the MFMA loop; s5c GELU 2/x divisions -> v_rcp_f32 form
# baseline (speedup 1.0000x reference)
.LBB0_318:
	ds_read_b128 v[130:133], v142
	ds_read_b128 v[198:201], v142 offset:64
	ds_read_b128 v[202:205], v142 offset:128
	ds_read_b128 v[234:237], v142 offset:192
	s_waitcnt lgkmcnt(3)
	v_mfma_f32_16x16x32_bf16 v[134:137], v[130:133], v[2:5], 0
	v_mfma_f32_16x16x32_bf16 v[130:133], v[130:133], v[6:9], 0
	ds_read_b128 v[144:147], v142 offset:256
	s_waitcnt lgkmcnt(3)
	v_mfma_f32_16x16x32_bf16 v[134:137], v[198:201], v[10:13], v[134:137]
	v_mfma_f32_16x16x32_bf16 v[130:133], v[198:201], v[14:17], v[130:133]
	ds_read_b128 v[198:201], v142 offset:320
	s_waitcnt lgkmcnt(3)
	v_mfma_f32_16x16x32_bf16 v[134:137], v[202:205], v[18:21], v[134:137]
	v_mfma_f32_16x16x32_bf16 v[130:133], v[202:205], v[22:25], v[130:133]
	ds_read_b128 v[202:205], v142 offset:384
	s_waitcnt lgkmcnt(3)
	v_mfma_f32_16x16x32_bf16 v[134:137], v[234:237], v[26:29], v[134:137]
	v_mfma_f32_16x16x32_bf16 v[130:133], v[234:237], v[30:33], v[130:133]
	ds_read_b128 v[234:237], v142 offset:448
	s_waitcnt lgkmcnt(3)
	v_mfma_f32_16x16x32_bf16 v[134:137], v[144:147], v[34:37], v[134:137]
	v_mfma_f32_16x16x32_bf16 v[130:133], v[144:147], v[38:41], v[130:133]
	ds_read_b128 v[144:147], v142 offset:512
	s_waitcnt lgkmcnt(3)
	v_mfma_f32_16x16x32_bf16 v[134:137], v[198:201], v[42:45], v[134:137]
	v_mfma_f32_16x16x32_bf16 v[130:133], v[198:201], v[46:49], v[130:133]
	ds_read_b128 v[198:201], v142 offset:576
	s_waitcnt lgkmcnt(3)
	v_mfma_f32_16x16x32_bf16 v[134:137], v[202:205], v[50:53], v[134:137]
	v_mfma_f32_16x16x32_bf16 v[130:133], v[202:205], v[54:57], v[130:133]
	ds_read_b128 v[202:205], v142 offset:640
	s_waitcnt lgkmcnt(3)
	v_mfma_f32_16x16x32_bf16 v[134:137], v[234:237], v[58:61], v[134:137]
	v_mfma_f32_16x16x32_bf16 v[130:133], v[234:237], v[62:65], v[130:133]
	ds_read_b128 v[234:237], v142 offset:704
	s_waitcnt lgkmcnt(3)
	v_mfma_f32_16x16x32_bf16 v[134:137], v[144:147], v[66:69], v[134:137]
	v_mfma_f32_16x16x32_bf16 v[130:133], v[144:147], v[74:77], v[130:133]
	ds_read_b128 v[144:147], v142 offset:768
	s_waitcnt lgkmcnt(3)
	v_mfma_f32_16x16x32_bf16 v[134:137], v[198:201], v[70:73], v[134:137]
	v_mfma_f32_16x16x32_bf16 v[130:133], v[198:201], v[78:81], v[130:133]
	ds_read_b128 v[198:201], v142 offset:832
	s_waitcnt lgkmcnt(3)
	v_mfma_f32_16x16x32_bf16 v[134:137], v[202:205], v[82:85], v[134:137]
	v_mfma_f32_16x16x32_bf16 v[130:133], v[202:205], v[90:93], v[130:133]
	ds_read_b128 v[202:205], v142 offset:896
	s_waitcnt lgkmcnt(3)
	v_mfma_f32_16x16x32_bf16 v[134:137], v[234:237], v[86:89], v[134:137]
	v_mfma_f32_16x16x32_bf16 v[130:133], v[234:237], v[94:97], v[130:133]
	ds_read_b128 v[234:237], v142 offset:960
	s_waitcnt lgkmcnt(3)
	v_mfma_f32_16x16x32_bf16 v[134:137], v[144:147], v[98:101], v[134:137]
	v_mfma_f32_16x16x32_bf16 v[130:133], v[144:147], v[106:109], v[130:133]
	s_waitcnt lgkmcnt(2)
	v_mfma_f32_16x16x32_bf16 v[134:137], v[198:201], v[102:105], v[134:137]
	v_mfma_f32_16x16x32_bf16 v[130:133], v[198:201], v[110:113], v[130:133]
	s_waitcnt lgkmcnt(1)
	v_mfma_f32_16x16x32_bf16 v[134:137], v[202:205], v[114:117], v[134:137]
	v_mfma_f32_16x16x32_bf16 v[130:133], v[202:205], v[122:125], v[130:133]
	s_waitcnt lgkmcnt(0)
	v_mfma_f32_16x16x32_bf16 v[134:137], v[234:237], v[118:121], v[134:137]
	v_mfma_f32_16x16x32_bf16 v[130:133], v[234:237], v[126:129], v[130:133]
	s_and_saveexec_b64 s[12:13], s[40:41]
	s_cbranch_execz .LBB0_320
	s_nop 4
	v_mul_f32_e32 v143, 0x3d372713, v134
	v_mul_f32_e32 v143, v134, v143
	v_fma_f32 v143, v134, v143, v134
	v_mul_f32_e32 v143, 0x3f4c422a, v143
	v_add_f32_e32 v143, v143, v143
	v_mul_f32_e32 v143, 0x3fb8aa3b, v143
	v_exp_f32_e32 v144, v143
	v_mul_f32_e32 v143, 0x3d372713, v135
	v_mul_f32_e32 v143, v135, v143
	v_fma_f32 v143, v135, v143, v135
	v_mul_f32_e32 v143, 0x3f4c422a, v143
	v_add_f32_e32 v143, v143, v143
	v_mul_f32_e32 v143, 0x3fb8aa3b, v143
	v_exp_f32_e32 v145, v143
	v_pk_mul_f32 v[134:135], v[134:135], 0.5 op_sel_hi:[1,0]
	v_pk_add_f32 v[144:145], v[144:145], 1.0 op_sel_hi:[1,0]
	s_nop 0
	v_rcp_f32_e32 v145, v145
	s_nop 0
	v_fma_f32 v145, v145, -2.0, 1.0
	v_rcp_f32_e32 v144, v144
	s_nop 0
	v_fma_f32 v144, v144, -2.0, 1.0
	s_nop 0
	v_pk_add_f32 v[144:145], v[144:145], 1.0 op_sel_hi:[1,0]
	s_nop 0
	v_pk_mul_f32 v[134:135], v[134:135], v[144:145]
	s_nop 0
	v_cvt_pk_bf16_f32 v134, v134, v135
	v_mul_f32_e32 v135, 0x3d372713, v136
	v_mul_f32_e32 v135, v136, v135
	v_fma_f32 v135, v136, v135, v136
	v_mul_f32_e32 v135, 0x3f4c422a, v135
	v_add_f32_e32 v135, v135, v135
	v_mul_f32_e32 v135, 0x3fb8aa3b, v135
	v_exp_f32_e32 v144, v135
	v_mul_f32_e32 v135, 0x3d372713, v137
	v_mul_f32_e32 v135, v137, v135
	v_fma_f32 v135, v137, v135, v137
	v_mul_f32_e32 v135, 0x3f4c422a, v135
	v_add_f32_e32 v135, v135, v135
	v_mul_f32_e32 v135, 0x3fb8aa3b, v135
	v_exp_f32_e32 v145, v135
	v_pk_mul_f32 v[136:137], v[136:137], 0.5 op_sel_hi:[1,0]
	v_pk_add_f32 v[144:145], v[144:145], 1.0 op_sel_hi:[1,0]
	s_nop 0
	v_rcp_f32_e32 v145, v145
	s_nop 0
	v_fma_f32 v145, v145, -2.0, 1.0
	v_rcp_f32_e32 v144, v144
	s_nop 0
	v_fma_f32 v144, v144, -2.0, 1.0
	s_nop 0
	v_pk_add_f32 v[144:145], v[144:145], 1.0 op_sel_hi:[1,0]
	s_nop 0
	v_pk_mul_f32 v[136:137], v[136:137], v[144:145]
	s_nop 0
	v_cvt_pk_bf16_f32 v135, v136, v137
	v_lshl_add_u64 v[136:137], v[138:139], 0, s[8:9]
	global_store_dwordx2 v[136:137], v[134:135], off
.LBB0_320:
	s_or_b64 exec, exec, s[12:13]
	s_and_saveexec_b64 s[12:13], s[42:43]
	s_cbranch_execz .LBB0_317
	s_nop 2
	v_mul_f32_e32 v134, 0x3d372713, v130
	v_mul_f32_e32 v135, 0x3d372713, v131
	v_mul_f32_e32 v134, v130, v134
	v_mul_f32_e32 v135, v131, v135
	v_fma_f32 v134, v130, v134, v130
	v_fma_f32 v135, v131, v135, v131
	v_mul_f32_e32 v134, 0x3f4c422a, v134
	v_mul_f32_e32 v135, 0x3f4c422a, v135
	v_add_f32_e32 v134, v134, v134
	v_add_f32_e32 v135, v135, v135
	v_mul_f32_e32 v134, 0x3fb8aa3b, v134
	v_mul_f32_e32 v135, 0x3fb8aa3b, v135
	v_exp_f32_e32 v134, v134
	v_exp_f32_e32 v135, v135
	v_pk_mul_f32 v[130:131], v[130:131], 0.5 op_sel_hi:[1,0]
	v_pk_add_f32 v[134:135], v[134:135], 1.0 op_sel_hi:[1,0]
	s_nop 0
	v_rcp_f32_e32 v135, v135
	s_nop 0
	v_fma_f32 v135, v135, -2.0, 1.0
	v_rcp_f32_e32 v134, v134
	s_nop 0
	v_fma_f32 v134, v134, -2.0, 1.0
	s_nop 0
	v_pk_add_f32 v[134:135], v[134:135], 1.0 op_sel_hi:[1,0]
	s_nop 0
	v_pk_mul_f32 v[130:131], v[130:131], v[134:135]
	s_nop 0
	v_cvt_pk_bf16_f32 v130, v130, v131
	v_mul_f32_e32 v131, 0x3d372713, v132
	v_mul_f32_e32 v131, v132, v131
	v_fma_f32 v131, v132, v131, v132
	v_mul_f32_e32 v131, 0x3f4c422a, v131
	v_add_f32_e32 v131, v131, v131
	v_mul_f32_e32 v131, 0x3fb8aa3b, v131
	v_exp_f32_e32 v134, v131
	v_mul_f32_e32 v131, 0x3d372713, v133
	v_mul_f32_e32 v131, v133, v131
	v_fma_f32 v131, v133, v131, v133
	v_mul_f32_e32 v131, 0x3f4c422a, v131
	v_add_f32_e32 v131, v131, v131
	v_mul_f32_e32 v131, 0x3fb8aa3b, v131
	v_exp_f32_e32 v135, v131
	v_pk_mul_f32 v[132:133], v[132:133], 0.5 op_sel_hi:[1,0]
	v_pk_add_f32 v[134:135], v[134:135], 1.0 op_sel_hi:[1,0]
	s_nop 0
	v_rcp_f32_e32 v135, v135
	s_nop 0
	v_fma_f32 v135, v135, -2.0, 1.0
	v_rcp_f32_e32 v134, v134
	s_nop 0
	v_fma_f32 v134, v134, -2.0, 1.0
	s_nop 0
	v_pk_add_f32 v[134:135], v[134:135], 1.0 op_sel_hi:[1,0]
	s_nop 0
	v_pk_mul_f32 v[132:133], v[132:133], v[134:135]
	s_nop 0
	v_cvt_pk_bf16_f32 v131, v132, v133
	v_lshl_add_u64 v[132:133], v[140:141], 0, s[8:9]
	global_store_dwordx2 v[132:133], v[130:131], off
	s_branch .LBB0_317
